# phase head: kernel arguments are fetched and parked in the v239 spill lanes only in the first phase (they are constant and nothing else writes those lanes); later phases skip the two scalar round trip
# speedup vs baseline: 1.0043x; 1.0042x over previous
.LBB0_11:
	v_readlane_b32 s4, v240, 1
	v_readlane_b32 s5, v240, 2
	v_readlane_b32 s3, v240, 0
	s_mov_b32 s78, s3
	v_readlane_b32 s3, v240, 55
	v_mov_b32_e32 v0, v165
	v_mbcnt_lo_u32_b32 v0, -1, v0
	v_mbcnt_hi_u32_b32 v211, -1, v0
	s_cmp_eq_u32 s101, 0
	s_cbranch_scc0 .Lhead_args_parked
	s_load_dwordx2 s[6:7], s[4:5], 0xe0
	s_load_dwordx8 s[8:15], s[4:5], 0xc0
	s_waitcnt lgkmcnt(0)
	v_writelane_b32 v239, s8, 21
	v_writelane_b32 v239, s9, 22
	v_writelane_b32 v239, s10, 23
	v_writelane_b32 v239, s11, 24
	v_writelane_b32 v239, s12, 25
	v_writelane_b32 v239, s13, 26
	v_writelane_b32 v239, s14, 27
	v_writelane_b32 v239, s15, 28
	s_load_dwordx16 s[8:23], s[4:5], 0x0
	v_writelane_b32 v239, s6, 29
	v_writelane_b32 v239, s7, 30
	s_waitcnt lgkmcnt(0)
	v_writelane_b32 v239, s8, 31
	v_writelane_b32 v239, s9, 32
	v_writelane_b32 v239, s10, 33
	v_writelane_b32 v239, s11, 34
	v_writelane_b32 v239, s12, 35
	v_writelane_b32 v239, s13, 36
	v_writelane_b32 v239, s14, 37
	v_writelane_b32 v239, s15, 38
	v_writelane_b32 v239, s16, 39
	v_writelane_b32 v239, s17, 40
	v_writelane_b32 v239, s18, 41
	v_writelane_b32 v239, s19, 42
	v_writelane_b32 v239, s20, 43
	v_writelane_b32 v239, s21, 44
	v_writelane_b32 v239, s22, 45
	v_writelane_b32 v239, s23, 46
.Lhead_args_parked:
	s_cmp_lt_i32 s70, 29
	s_mov_b64 s[6:7], -1
	v_add_u32_e32 v210, s3, v211
	s_load_dwordx16 s[16:31], s[4:5], 0x40
	s_load_dwordx16 s[36:51], s[4:5], 0x80
	s_mov_b64 s[12:13], 0
	s_mov_b64 s[4:5], 0
	s_cbranch_scc1 .LBB0_28
	s_cmp_eq_u32 s70, 29
	s_mov_b64 s[4:5], -1
	s_cbranch_scc0 .LBB0_32
	s_waitcnt lgkmcnt(0)
	v_readlane_b32 s34, v239, 29
	v_readlane_b32 s35, v239, 30
	v_readlane_b32 s14, v239, 25
	v_readlane_b32 s15, v239, 26
	v_and_b32_e32 v8, 63, v211
	v_lshlrev_b32_e32 v0, 5, v8
	v_lshlrev_b32_e32 v1, 4, v8
	v_lshlrev_b32_e32 v9, 2, v8
	v_xor_b32_e32 v2, 0x4, v9
	v_xor_b32_e32 v3, 0x8, v9
	v_xor_b32_e32 v4, 0x10, v9
	v_xor_b32_e32 v5, 0x20, v9
	v_xor_b32_e32 v6, 0x40, v9
	v_xor_b32_e32 v7, 0x80, v9
	v_readlane_b32 s3, v240, 55
	v_readlane_b32 s6, v239, 10
	s_lshr_b32 s3, s3, 6
	s_lshl_b32 s3, s3, 2
	s_and_b32 s7, s78, 7
	s_lshl_b32 s7, s7, 10
	s_add_i32 s3, s3, s7
	s_bfe_u32 s7, s78, 0x20003
	s_lshl_b32 s7, s7, 8
	s_add_i32 s3, s3, s7
	s_lshr_b32 s7, s78, 5
	s_lshl_b32 s7, s7, 5
	s_add_i32 s3, s3, s7
	s_lshl_b32 s6, s6, 3
	s_cmpk_lt_i32 s3, 0x2000
	s_cbranch_scc0 .LnormF_end
